# v37
# speedup vs baseline: 1.0003x; 1.0003x over previous
_Z14fwd_megakernel6Params:
	s_load_dword s3, s[0:1], 0x150
	v_and_b32_e32 v1, 0x3ff, v0
	s_add_u32 s10, s0, 0x150
	v_readfirstlane_b32 s40, v1
	s_addc_u32 s11, s1, 0
	s_and_b32 s33, s40, 0xffffffc0
	s_cmp_lt_u32 s33, 0x100
	s_cbranch_scc0 .Lprio_entry
	s_setprio 1

.LBB0_551:
	s_or_b64 exec, exec, s[4:5]
	s_mov_b32 s8, s2
	s_barrier
	s_cmp_lt_u32 s33, 0x100
	s_cbranch_scc0 .Lprio_post
	s_setprio 1
